# prep phase: each prep_w call's tile list starts at a rotated workgroup half (cumulative tile count mod 512) so weight-conversion tiles are dealt round-robin over all halves instead of piling on halves
# speedup vs baseline: 1.0207x; 1.0164x over previous
; DI int vbid() { return (int)blockIdx.x * 2 + half_(); }
; DI int vgrid() { return (int)gridDim.x * 2; }
; DI void prep_w(const float* __restrict__ src, int K, int N, u16* __restrict__ dst, int Npad, const float* __restrict__ g, int perm,
;                u16* T) {
;     ...
;   const int ntn = Npad >> 6, ntiles = (K >> 6) * ntn;
;   for (int it = vbid(); it < ntiles; it += vgrid()) {
;     const int kt = it / ntn, k0 = kt * 64, n0 = (it - kt * ntn) * 64;
;     int sn0 = n0;
;     if (perm) { int tl = n0 >> 7, rr = n0 & 127; sn0 = (rr < 64) ? (tl * 64 + rr) : (256 + tl * 64 + rr - 64); }
; DI void phase_prep(PREF p, unsigned char* ldsb) {
;     ...
;   for (int l = 0; l < NL; ++l) {
;     u16* W = p.wts + (size_t)l * WL;
;     prep_w(p.w_in + (size_t)l * 1024 * HW, 1024, HW, W + O_WIN, 2816, nullptr, 0, T);
.LBB0_490:
	s_mul_i32 s1, s44, 0x14b0000
	s_mul_hi_u32 s0, s44, 0x14b0000
	s_add_u32 s46, s10, s1
	s_addc_u32 s47, s11, s0
	v_readfirstlane_b32 s0, v168
	s_lshr_b32 s8, s0, 8
	s_add_i32 s52, s8, s70
	s_cmpk_lg_u32 s71, 0x200
	s_cbranch_scc1 .Lmy_rot_0
	s_mul_i32 s98, s44, 0x58
	s_addk_i32 s98, 0x0
	s_sub_i32 s52, s52, s98
	s_and_b32 s52, s52, 0x1ff
.Lmy_rot_0:
	s_mov_b32 s45, s53
	v_mov_b32_e32 v6, v169
	s_cmpk_gt_i32 s52, 0x2bf
	s_cbranch_scc1 .LBB0_525
	s_mul_i32 s1, s44, 0xaa0000
	s_mul_hi_u32 s0, s44, 0xaa0000
	s_add_u32 s48, s20, s1
	v_and_b32_e32 v3, 63, v6
	s_addc_u32 s49, s21, s0
	v_lshlrev_b32_e32 v0, 2, v3
	v_lshl_add_u64 v[4:5], s[48:49], 0, v[0:1]
	v_lshlrev_b32_e32 v0, 4, v6
	v_and_b32_e32 v0, 48, v0
	v_ashrrev_i32_e32 v8, 6, v6
	v_ashrrev_i32_e32 v9, 2, v6
	v_mul_u32_u24_e32 v6, 0x48, v0
	v_lshlrev_b32_e32 v6, 1, v6
	v_lshlrev_b32_e32 v7, 1, v9
	v_add3_u32 v10, s33, v6, v7
	v_mul_lo_u32 v6, v8, s97
	v_lshlrev_b32_e32 v7, 1, v3
	s_lshl_b32 s0, s8, 6
	v_add3_u32 v11, s33, v6, v7
	s_lshl_b32 s55, s52, 6
	v_lshlrev_b32_e32 v0, 1, v0
	s_branch .LBB0_493

; DI int vbid() { return (int)blockIdx.x * 2 + half_(); }
; DI int vgrid() { return (int)gridDim.x * 2; }
; DI void prep_w(const float* __restrict__ src, int K, int N, u16* __restrict__ dst, int Npad, const float* __restrict__ g, int perm,
;                u16* T) {
;     ...
;   const int ntn = Npad >> 6, ntiles = (K >> 6) * ntn;
;   for (int it = vbid(); it < ntiles; it += vgrid()) {
;     const int kt = it / ntn, k0 = kt * 64, n0 = (it - kt * ntn) * 64;
;     int sn0 = n0;
; DI void phase_prep(PREF p, unsigned char* ldsb) {
;     ...
;     prep_w(p.w_merge + (size_t)l * 1024 * 4096, 1024, 4096, W + O_WM, 4096, nullptr, 0, T);
.LBB0_525:
	v_readfirstlane_b32 s0, v168
	s_lshr_b32 s8, s0, 8
	s_add_i32 s52, s8, s70
	s_cmpk_lg_u32 s71, 0x200
	s_cbranch_scc1 .Lmy_rot_1
	s_mul_i32 s98, s44, 0x58
	s_addk_i32 s98, 0xc0
	s_sub_i32 s52, s52, s98
	s_and_b32 s52, s52, 0x1ff
.Lmy_rot_1:
	v_mov_b32_e32 v6, v169
	s_cmpk_gt_i32 s52, 0x3ff
	s_cbranch_scc1 .LBB0_560
	s_add_u32 s48, s46, 0x580000
	s_addc_u32 s49, s47, 0
	s_lshl_b64 s[56:57], s[44:45], 24
	s_add_u32 s56, s22, s56
	v_and_b32_e32 v3, 63, v6
	s_addc_u32 s57, s23, s57
	v_lshlrev_b32_e32 v0, 2, v3
	v_lshl_add_u64 v[4:5], s[56:57], 0, v[0:1]
	v_lshlrev_b32_e32 v0, 4, v6
	v_and_b32_e32 v0, 48, v0
	v_ashrrev_i32_e32 v10, 6, v6
	v_ashrrev_i32_e32 v11, 2, v6
	v_mul_u32_u24_e32 v6, 0x48, v0
	v_lshlrev_b32_e32 v6, 1, v6
	v_lshlrev_b32_e32 v7, 1, v11
	v_add3_u32 v12, s33, v6, v7
	v_mul_lo_u32 v6, v10, s97
	v_lshlrev_b32_e32 v7, 1, v3
	s_lshl_b32 s0, s8, 6
	v_add3_u32 v13, s33, v6, v7
	s_lshl_b32 s55, s52, 6
	v_lshlrev_b32_e32 v0, 1, v0
	s_branch .LBB0_528

; DI int vbid() { return (int)blockIdx.x * 2 + half_(); }
; DI int vgrid() { return (int)gridDim.x * 2; }
; DI void prep_w(const float* __restrict__ src, int K, int N, u16* __restrict__ dst, int Npad, const float* __restrict__ g, int perm,
;                u16* T) {
;     ...
;   const int ntn = Npad >> 6, ntiles = (K >> 6) * ntn;
;   for (int it = vbid(); it < ntiles; it += vgrid()) {
;     const int kt = it / ntn, k0 = kt * 64, n0 = (it - kt * ntn) * 64;
;     int sn0 = n0;
; DI void phase_prep(PREF p, unsigned char* ldsb) {
;     ...
;     prep_w(p.w_pw2 + (size_t)l * 65536, 256, 256, W + O_PW2, 256, nullptr, 0, T);
.LBB0_560:
	v_readfirstlane_b32 s0, v168
	s_lshr_b32 s8, s0, 8
	s_lshl_b64 s[48:49], s[44:45], 18
	s_add_i32 s52, s8, s70
	s_cmpk_lg_u32 s71, 0x200
	s_cbranch_scc1 .Lmy_rot_2
	s_mul_i32 s98, s44, 0x58
	s_addk_i32 s98, 0xc0
	s_sub_i32 s52, s52, s98
	s_and_b32 s52, s52, 0x1ff
.Lmy_rot_2:
	v_mov_b32_e32 v6, v169
	s_cmp_gt_i32 s52, 15
	s_cbranch_scc1 .LBB0_595
	s_add_u32 s62, s46, 0xd80000
	s_addc_u32 s63, s47, 0
	s_add_u32 s56, s12, s48
	v_and_b32_e32 v3, 63, v6
	s_addc_u32 s57, s13, s49
	v_lshlrev_b32_e32 v0, 2, v3
	v_lshl_add_u64 v[4:5], s[56:57], 0, v[0:1]
	v_lshlrev_b32_e32 v0, 4, v6
	v_and_b32_e32 v0, 48, v0
	v_ashrrev_i32_e32 v10, 6, v6
	v_ashrrev_i32_e32 v11, 2, v6
	v_mul_u32_u24_e32 v6, 0x48, v0
	v_lshlrev_b32_e32 v6, 1, v6
	v_lshlrev_b32_e32 v7, 1, v11
	v_add3_u32 v12, s33, v6, v7
	v_mul_lo_u32 v6, v10, s97
	v_lshlrev_b32_e32 v7, 1, v3
	s_lshl_b32 s0, s8, 6
	v_add3_u32 v13, s33, v6, v7
	s_lshl_b32 s55, s52, 6
	v_lshlrev_b32_e32 v0, 1, v0
	s_branch .LBB0_563

; DI int vbid() { return (int)blockIdx.x * 2 + half_(); }
; DI int vgrid() { return (int)gridDim.x * 2; }
; DI void prep_w(const float* __restrict__ src, int K, int N, u16* __restrict__ dst, int Npad, const float* __restrict__ g, int perm,
;                u16* T) {
;     ...
;   const int ntn = Npad >> 6, ntiles = (K >> 6) * ntn;
;   for (int it = vbid(); it < ntiles; it += vgrid()) {
;     const int kt = it / ntn, k0 = kt * 64, n0 = (it - kt * ntn) * 64;
;     int sn0 = n0;
; DI void phase_prep(PREF p, unsigned char* ldsb) {
;     ...
;     prep_w(p.w_uq + (size_t)l * 256 * 384, 256, 384, W + O_UQ, 384, p.qng + l * 256, 0, T);
.LBB0_595:
	v_readfirstlane_b32 s0, v168
	s_lshr_b32 s56, s0, 8
	s_add_i32 s55, s56, s70
	s_cmpk_lg_u32 s71, 0x200
	s_cbranch_scc1 .Lmy_rot_3
	s_mul_i32 s98, s44, 0x58
	s_addk_i32 s98, 0xd0
	s_sub_i32 s55, s55, s98
	s_and_b32 s55, s55, 0x1ff
.Lmy_rot_3:
	v_mov_b32_e32 v6, v169
	s_cmp_gt_i32 s55, 23
	s_cbranch_scc1 .LBB0_632
	s_add_u32 s8, s46, 0xda0000
	s_addc_u32 s9, s47, 0
	s_lshl_b32 s52, s44, 8
	s_lshl_b64 s[62:63], s[52:53], 2
	s_add_u32 s62, s14, s62
	s_addc_u32 s63, s15, s63
	s_mul_i32 s1, s44, 0x60000
	s_mul_hi_u32 s0, s44, 0x60000
	s_add_u32 s64, s18, s1
	v_and_b32_e32 v3, 63, v6
	s_addc_u32 s65, s19, s0
	v_lshlrev_b32_e32 v0, 2, v3
	v_lshl_add_u64 v[4:5], s[64:65], 0, v[0:1]
	v_lshlrev_b32_e32 v0, 4, v6
	v_and_b32_e32 v0, 48, v0
	v_ashrrev_i32_e32 v26, 6, v6
	v_ashrrev_i32_e32 v27, 2, v6
	v_mul_u32_u24_e32 v6, 0x48, v0
	v_lshlrev_b32_e32 v6, 1, v6
	v_lshlrev_b32_e32 v7, 1, v27
	v_add3_u32 v28, s33, v6, v7
	v_mul_lo_u32 v6, v26, s97
	v_lshlrev_b32_e32 v7, 1, v3
	s_lshl_b32 s0, s56, 6
	v_add3_u32 v29, s33, v6, v7
	s_lshl_b32 s52, s55, 6
	v_lshlrev_b32_e32 v0, 1, v0
	s_branch .LBB0_598

; DI int vbid() { return (int)blockIdx.x * 2 + half_(); }
; DI int vgrid() { return (int)gridDim.x * 2; }
; DI void prep_w(const float* __restrict__ src, int K, int N, u16* __restrict__ dst, int Npad, const float* __restrict__ g, int perm,
;                u16* T) {
;     ...
;   const int ntn = Npad >> 6, ntiles = (K >> 6) * ntn;
;   for (int it = vbid(); it < ntiles; it += vgrid()) {
;     const int kt = it / ntn, k0 = kt * 64, n0 = (it - kt * ntn) * 64;
;     int sn0 = n0;
; DI void phase_prep(PREF p, unsigned char* ldsb) {
;     ...
;     prep_w(p.w_ukv + (size_t)l * 128 * 512, 128, 512, W + O_UKV, 512, p.kvng + l * 128, 0, T);
.LBB0_632:
	v_readfirstlane_b32 s0, v168
	s_lshr_b32 s8, s0, 8
	s_add_i32 s64, s8, s70
	s_cmpk_lg_u32 s71, 0x200
	s_cbranch_scc1 .Lmy_rot_4
	s_mul_i32 s98, s44, 0x58
	s_addk_i32 s98, 0xe8
	s_sub_i32 s64, s64, s98
	s_and_b32 s64, s64, 0x1ff
.Lmy_rot_4:
	v_mov_b32_e32 v6, v169
	s_cmp_gt_i32 s64, 15
	s_cbranch_scc1 .LBB0_669
	s_add_u32 s68, s46, 0xdd0000
	s_addc_u32 s69, s47, 0
	s_lshl_b32 s52, s44, 7
	s_lshl_b64 s[0:1], s[52:53], 2
	s_add_u32 s62, s16, s0
	s_addc_u32 s63, s17, s1
	s_add_u32 s0, s34, s48
	v_and_b32_e32 v3, 63, v6
	s_addc_u32 s1, s35, s49
	v_lshlrev_b32_e32 v0, 2, v3
	v_lshl_add_u64 v[4:5], s[0:1], 0, v[0:1]
	v_lshlrev_b32_e32 v0, 4, v6
	v_and_b32_e32 v0, 48, v0
	v_ashrrev_i32_e32 v26, 6, v6
	v_ashrrev_i32_e32 v27, 2, v6
	v_mul_u32_u24_e32 v6, 0x48, v0
	v_lshlrev_b32_e32 v6, 1, v6
	v_lshlrev_b32_e32 v7, 1, v27
	v_add3_u32 v28, s33, v6, v7
	v_mul_lo_u32 v6, v26, s97
	v_lshlrev_b32_e32 v7, 1, v3
	s_lshl_b32 s0, s8, 6
	v_add3_u32 v29, s33, v6, v7
	s_lshl_b32 s52, s64, 6
	v_lshlrev_b32_e32 v0, 1, v0
	s_branch .LBB0_635

; DI int vbid() { return (int)blockIdx.x * 2 + half_(); }
; DI int vgrid() { return (int)gridDim.x * 2; }
; DI void prep_w(const float* __restrict__ src, int K, int N, u16* __restrict__ dst, int Npad, const float* __restrict__ g, int perm,
;                u16* T) {
;     ...
;   const int ntn = Npad >> 6, ntiles = (K >> 6) * ntn;
;   for (int it = vbid(); it < ntiles; it += vgrid()) {
;     const int kt = it / ntn, k0 = kt * 64, n0 = (it - kt * ntn) * 64;
;     int sn0 = n0;
;     if (perm) { int tl = n0 >> 7, rr = n0 & 127; sn0 = (rr < 64) ? (tl * 64 + rr) : (256 + tl * 64 + rr - 64); }
; DI void phase_prep(PREF p, unsigned char* ldsb) {
;     ...
;     prep_w(p.w_glu + (size_t)l * 256 * 512, 256, 512, W + O_GLU, 512, nullptr, 1, T);
.LBB0_669:
	v_readfirstlane_b32 s0, v168
	s_lshr_b32 s8, s0, 8
	s_add_i32 s52, s8, s70
	s_cmpk_lg_u32 s71, 0x200
	s_cbranch_scc1 .Lmy_rot_5
	s_mul_i32 s98, s44, 0x58
	s_addk_i32 s98, 0xf8
	s_sub_i32 s52, s52, s98
	s_and_b32 s52, s52, 0x1ff
.Lmy_rot_5:
	v_mov_b32_e32 v6, v169
	s_cmp_gt_i32 s52, 31
	s_cbranch_scc1 .LBB0_704
	s_add_u32 s48, s46, 0xdf0000
	s_addc_u32 s49, s47, 0
	s_lshl_b64 s[0:1], s[44:45], 19
	s_add_u32 s0, s36, s0
	v_and_b32_e32 v3, 63, v6
	s_addc_u32 s1, s37, s1
	v_lshlrev_b32_e32 v0, 2, v3
	v_lshl_add_u64 v[4:5], s[0:1], 0, v[0:1]
	v_lshlrev_b32_e32 v0, 4, v6
	v_and_b32_e32 v0, 48, v0
	v_ashrrev_i32_e32 v10, 6, v6
	v_ashrrev_i32_e32 v11, 2, v6
	v_mul_u32_u24_e32 v6, 0x48, v0
	v_lshlrev_b32_e32 v6, 1, v6
	v_lshlrev_b32_e32 v7, 1, v11
	s_lshl_b32 s0, s8, 5
	v_readlane_b32 s1, v254, 25
	v_add3_u32 v12, s33, v6, v7
	v_mul_lo_u32 v6, v10, s97
	v_lshlrev_b32_e32 v7, 1, v3
	s_lshl_b32 s55, s52, 5
	s_lshl_b32 s0, s8, 6
	v_add3_u32 v13, s33, v6, v7
	s_lshl_b32 s64, s52, 6
	v_lshlrev_b32_e32 v0, 1, v0
	s_branch .LBB0_672

; DI int vbid() { return (int)blockIdx.x * 2 + half_(); }
; DI int vgrid() { return (int)gridDim.x * 2; }
; DI void prep_w(const float* __restrict__ src, int K, int N, u16* __restrict__ dst, int Npad, const float* __restrict__ g, int perm,
;                u16* T) {
;     ...
;   const int ntn = Npad >> 6, ntiles = (K >> 6) * ntn;
;   for (int it = vbid(); it < ntiles; it += vgrid()) {
;     const int kt = it / ntn, k0 = kt * 64, n0 = (it - kt * ntn) * 64;
;     int sn0 = n0;
; DI void phase_prep(PREF p, unsigned char* ldsb) {
;     ...
;     for (int nb = 0; nb < 4; ++nb)
;       prep_w(p.w_branch + ((size_t)l * 4 + nb) * 256 * 1024, 256, 1024, W + O_BR + (size_t)nb * 1024 * 256, 1024, nullptr, 0, T);
.LBB0_706:
	v_readfirstlane_b32 s0, v168
	s_lshr_b32 s8, s0, 8
	s_add_i32 s55, s8, s70
	s_cmpk_lg_u32 s71, 0x200
	s_cbranch_scc1 .Lmy_rot_6
	s_mul_i32 s98, s44, 0x58
	s_addk_i32 s98, 0x118
	s_lshl_b32 s99, s52, 6
	s_add_i32 s98, s98, s99
	s_sub_i32 s55, s55, s98
	s_and_b32 s55, s55, 0x1ff
.Lmy_rot_6:
	v_mov_b32_e32 v6, v169
	s_cmp_gt_i32 s55, 63
	s_cbranch_scc1 .LBB0_705
	s_lshl_b64 s[0:1], s[52:53], 19
	s_add_u32 s48, s64, s0
	s_addc_u32 s49, s65, s1
	s_lshl_b64 s[0:1], s[52:53], 20
	s_add_u32 s0, s68, s0
	v_and_b32_e32 v3, 63, v6
	s_addc_u32 s1, s69, s1
	v_lshlrev_b32_e32 v0, 2, v3
	v_lshl_add_u64 v[4:5], s[0:1], 0, v[0:1]
	v_lshlrev_b32_e32 v0, 4, v6
	v_and_b32_e32 v0, 48, v0
	v_ashrrev_i32_e32 v10, 6, v6
	v_ashrrev_i32_e32 v11, 2, v6
	v_mul_u32_u24_e32 v6, 0x48, v0
	v_lshlrev_b32_e32 v6, 1, v6
	v_lshlrev_b32_e32 v7, 1, v11
	v_add3_u32 v12, s33, v6, v7
	v_mul_lo_u32 v6, v10, s97
	v_lshlrev_b32_e32 v7, 1, v3
	s_lshl_b32 s0, s8, 6
	v_add3_u32 v13, s33, v6, v7
	s_lshl_b32 s61, s55, 6
	v_lshlrev_b32_e32 v0, 1, v0
	s_branch .LBB0_709

; DI int vbid() { return (int)blockIdx.x * 2 + half_(); }
; DI int vgrid() { return (int)gridDim.x * 2; }
; DI void prep_w(const float* __restrict__ src, int K, int N, u16* __restrict__ dst, int Npad, const float* __restrict__ g, int perm,
;                u16* T) {
;     ...
;   const int ntn = Npad >> 6, ntiles = (K >> 6) * ntn;
;   for (int it = vbid(); it < ntiles; it += vgrid()) {
;     const int kt = it / ntn, k0 = kt * 64, n0 = (it - kt * ntn) * 64;
;     int sn0 = n0;
; DI void phase_prep(PREF p, unsigned char* ldsb) {
;     ...
;     prep_w(p.w_out + (size_t)l * 1048576, 1024, 1024, W + O_OUT, 1024, nullptr, 0, T);
.LBB0_741:
	v_readfirstlane_b32 s0, v168
	s_lshr_b32 s8, s0, 8
	v_readlane_b32 s64, v254, 44
	s_lshl_b64 s[48:49], s[44:45], 20
	s_add_i32 s45, s8, s70
	s_cmpk_lg_u32 s71, 0x200
	s_cbranch_scc1 .Lmy_rot_7
	s_mul_i32 s98, s44, 0x58
	s_addk_i32 s98, 0x18
	s_sub_i32 s45, s45, s98
	s_and_b32 s45, s45, 0x1ff
.Lmy_rot_7:
	v_readlane_b32 s65, v254, 45
	v_mov_b32_e32 v6, v169
	s_cmpk_gt_i32 s45, 0xff
	s_mov_b32 s61, 0x800000
	s_mov_b32 s65, 0x3fb8aa3b
	s_cbranch_scc1 .LBB0_776
	s_add_u32 s62, s46, 0x1030000
	s_addc_u32 s63, s47, 0
	s_lshl_b64 s[0:1], s[48:49], 2
	s_add_u32 s0, s26, s0
	v_and_b32_e32 v3, 63, v6
	s_addc_u32 s1, s27, s1
	v_lshlrev_b32_e32 v0, 2, v3
	v_lshl_add_u64 v[4:5], s[0:1], 0, v[0:1]
	v_lshlrev_b32_e32 v0, 4, v6
	v_and_b32_e32 v0, 48, v0
	v_ashrrev_i32_e32 v10, 6, v6
	v_ashrrev_i32_e32 v11, 2, v6
	v_mul_u32_u24_e32 v6, 0x48, v0
	v_lshlrev_b32_e32 v6, 1, v6
	v_lshlrev_b32_e32 v7, 1, v11
	v_add3_u32 v12, s33, v6, v7
	v_mul_lo_u32 v6, v10, s97
	v_lshlrev_b32_e32 v7, 1, v3
	s_lshl_b32 s0, s8, 6
	v_add3_u32 v13, s33, v6, v7
	s_lshl_b32 s52, s45, 6
	v_lshlrev_b32_e32 v0, 1, v0
	s_branch .LBB0_744

; DI int vbid() { return (int)blockIdx.x * 2 + half_(); }
; DI int vgrid() { return (int)gridDim.x * 2; }
; DI void prep_w(const float* __restrict__ src, int K, int N, u16* __restrict__ dst, int Npad, const float* __restrict__ g, int perm,
;                u16* T) {
;     ...
;   const int ntn = Npad >> 6, ntiles = (K >> 6) * ntn;
;   for (int it = vbid(); it < ntiles; it += vgrid()) {
;     const int kt = it / ntn, k0 = kt * 64, n0 = (it - kt * ntn) * 64;
;     int sn0 = n0;
; DI void phase_prep(PREF p, unsigned char* ldsb) {
;     ...
;     prep_w(p.w_ple + (size_t)l * 262144, 256, 1024, W + O_PLE, 1024, nullptr, 0, T);
.LBB0_776:
	v_readfirstlane_b32 s0, v168
	s_lshr_b32 s8, s0, 8
	s_add_i32 s45, s8, s70
	s_cmpk_lg_u32 s71, 0x200
	s_cbranch_scc1 .Lmy_rot_8
	s_mul_i32 s98, s44, 0x58
	s_addk_i32 s98, 0x118
	s_sub_i32 s45, s45, s98
	s_and_b32 s45, s45, 0x1ff
.Lmy_rot_8:
	v_mov_b32_e32 v6, v169
	s_cmp_gt_i32 s45, 63
	s_cbranch_scc1 .LBB0_811
	s_add_u32 s62, s46, 0x1230000
	s_addc_u32 s63, s47, 0
	s_add_u32 s0, s28, s48
	v_and_b32_e32 v3, 63, v6
	s_addc_u32 s1, s29, s49
	v_lshlrev_b32_e32 v0, 2, v3
	v_lshl_add_u64 v[4:5], s[0:1], 0, v[0:1]
	v_lshlrev_b32_e32 v0, 4, v6
	v_and_b32_e32 v0, 48, v0
	v_ashrrev_i32_e32 v10, 6, v6
	v_ashrrev_i32_e32 v11, 2, v6
	v_mul_u32_u24_e32 v6, 0x48, v0
	v_lshlrev_b32_e32 v6, 1, v6
	v_lshlrev_b32_e32 v7, 1, v11
	v_add3_u32 v12, s33, v6, v7
	v_mul_lo_u32 v6, v10, s97
	v_lshlrev_b32_e32 v7, 1, v3
	s_lshl_b32 s0, s8, 6
	v_add3_u32 v13, s33, v6, v7
	s_lshl_b32 s52, s45, 6
	v_lshlrev_b32_e32 v0, 1, v0
	s_branch .LBB0_779

; DI int vbid() { return (int)blockIdx.x * 2 + half_(); }
; DI int vgrid() { return (int)gridDim.x * 2; }
; DI void prep_w(const float* __restrict__ src, int K, int N, u16* __restrict__ dst, int Npad, const float* __restrict__ g, int perm,
;                u16* T) {
;     ...
;   const int ntn = Npad >> 6, ntiles = (K >> 6) * ntn;
;   for (int it = vbid(); it < ntiles; it += vgrid()) {
;     const int kt = it / ntn, k0 = kt * 64, n0 = (it - kt * ntn) * 64;
;     int sn0 = n0;
; DI void phase_prep(PREF p, unsigned char* ldsb) {
;     ...
;     prep_w(p.w_pleg + (size_t)l * 1048576, 1024, 1024, W + O_PLEG, 1024, nullptr, 0, T);
.LBB0_811:
	v_readfirstlane_b32 s0, v168
	s_lshr_b32 s8, s0, 8
	s_add_i32 s45, s8, s70
	s_cmpk_lg_u32 s71, 0x200
	s_cbranch_scc1 .Lmy_rot_9
	s_mul_i32 s98, s44, 0x58
	s_addk_i32 s98, 0x158
	s_sub_i32 s45, s45, s98
	s_and_b32 s45, s45, 0x1ff
.Lmy_rot_9:
	v_mov_b32_e32 v6, v169
	s_cmpk_gt_i32 s45, 0xff
	s_cbranch_scc1 .LBB0_489
	s_add_u32 s46, s46, 0x12b0000
	s_addc_u32 s47, s47, 0
	s_lshl_b64 s[0:1], s[48:49], 2
	s_add_u32 s0, s30, s0
	v_and_b32_e32 v3, 63, v6
	s_addc_u32 s1, s31, s1
	v_lshlrev_b32_e32 v0, 2, v3
	v_lshl_add_u64 v[4:5], s[0:1], 0, v[0:1]
	v_lshlrev_b32_e32 v0, 4, v6
	v_and_b32_e32 v0, 48, v0
	v_ashrrev_i32_e32 v10, 6, v6
	v_ashrrev_i32_e32 v11, 2, v6
	v_mul_u32_u24_e32 v6, 0x48, v0
	v_lshlrev_b32_e32 v6, 1, v6
	v_lshlrev_b32_e32 v7, 1, v11
	v_add3_u32 v12, s33, v6, v7
	v_mul_lo_u32 v6, v10, s97
	v_lshlrev_b32_e32 v7, 1, v3
	s_lshl_b32 s0, s8, 6
	v_add3_u32 v13, s33, v6, v7
	s_lshl_b32 s52, s45, 6
	v_lshlrev_b32_e32 v0, 1, v0
	s_branch .LBB0_814
